# v103: v100 + acquire invalidate (buffer_inv sc1) issued right after the arrival atomic so its latency overlaps the barrier wait; tail keeps only the drain
# speedup vs baseline: 1.0112x; 1.0112x over previous
.LBB0_138:
	s_or_b64 exec, exec, s[16:17]
	buffer_inv sc1
	v_cvt_f32_u32_e32 v4, v2
	s_waitcnt vmcnt(1)
	v_readfirstlane_b32 s3, v3
	v_sub_u32_e32 v3, 0, v2
	v_rcp_iflag_f32_e32 v4, v4
	v_add_u32_e32 v5, s3, v1
	v_mul_f32_e32 v4, 0x4f7ffffe, v4
	v_cvt_u32_f32_e32 v4, v4
	v_mul_lo_u32 v1, v3, v4
	v_mul_hi_u32 v1, v4, v1
	v_add_u32_e32 v1, v4, v1
	v_mul_hi_u32 v1, v5, v1
	v_mul_lo_u32 v3, v1, v2
	v_sub_u32_e32 v3, v5, v3
	v_add_u32_e32 v4, 1, v1
	v_cmp_ge_u32_e32 vcc, v3, v2
	s_nop 1
	v_cndmask_b32_e32 v1, v1, v4, vcc
	v_sub_u32_e32 v4, v3, v2
	v_cndmask_b32_e32 v3, v3, v4, vcc
	v_add_u32_e32 v4, 1, v1
	v_cmp_ge_u32_e32 vcc, v3, v2
	v_add_u32_e32 v3, 1, v5
	s_nop 0
	v_cndmask_b32_e32 v1, v1, v4, vcc
	v_mul_lo_u32 v4, v2, v1
	v_add_u32_e32 v2, v4, v2
	v_cmp_ne_u32_e32 vcc, v3, v2
	s_waitcnt lgkmcnt(0)
	v_mul_lo_u32 v4, v1, v0
	v_add_u32_e32 v4, v4, v0
	v_mov_b32_e32 v5, 0x2480
	s_cbranch_vccnz .Lsb_poll0
	buffer_wbl2 sc1
	s_waitcnt vmcnt(0)
	s_add_u32 s16, s10, 0x62480
	s_addc_u32 s17, s11, 0
	v_mov_b32_e32 v6, 0
	v_mov_b32_e32 v7, 1
	global_atomic_add v6, v7, s[16:17]
	global_atomic_add v6, v7, s[16:17] offset:256
	global_atomic_add v6, v7, s[16:17] offset:512
	global_atomic_add v6, v7, s[16:17] offset:768
	global_atomic_add v6, v7, s[16:17] offset:1024
	global_atomic_add v6, v7, s[16:17] offset:1280
	global_atomic_add v6, v7, s[16:17] offset:1536
	global_atomic_add v6, v7, s[16:17] offset:1792
	global_atomic_add v6, v7, s[16:17] offset:2048
	global_atomic_add v6, v7, s[16:17] offset:2304
	global_atomic_add v6, v7, s[16:17] offset:2560
	global_atomic_add v6, v7, s[16:17] offset:2816
	global_atomic_add v6, v7, s[16:17] offset:3072
	global_atomic_add v6, v7, s[16:17] offset:3328
	global_atomic_add v6, v7, s[16:17] offset:3584
	global_atomic_add v6, v7, s[16:17] offset:3840

.Lsb_loop0:
	global_load_dword v3, v5, s[12:13] sc1
	s_waitcnt vmcnt(0)
	v_cmp_ge_u32_e32 vcc, v3, v4
	s_cbranch_vccnz .Lsb_done0
	s_sleep 1
	s_add_i32 s3, s3, 1
	s_cmp_lt_u32 s3, 0x100000
	s_cbranch_scc1 .Lsb_loop0
.Lsb_done0:
	s_waitcnt vmcnt(0)
.LBB0_172:
	s_or_b64 exec, exec, s[8:9]
	s_waitcnt lgkmcnt(0)
	s_barrier

.Lsb_loop1:
	global_load_dword v3, v5, s[12:13] sc1
	s_waitcnt vmcnt(0)
	v_cmp_ge_u32_e32 vcc, v3, v4
	s_cbranch_vccnz .Lsb_done1
	s_sleep 1
	s_add_i32 s3, s3, 1
	s_cmp_lt_u32 s3, 0x100000
	s_cbranch_scc1 .Lsb_loop1
.Lsb_done1:
	s_waitcnt vmcnt(0)
.LBB0_270:
	s_or_b64 exec, exec, s[8:9]
	s_waitcnt lgkmcnt(0)
	s_barrier

.Lsb_loop2:
	global_load_dword v3, v5, s[12:13] sc1
	s_waitcnt vmcnt(0)
	v_cmp_ge_u32_e32 vcc, v3, v4
	s_cbranch_vccnz .Lsb_done2
	s_sleep 1
	s_add_i32 s3, s3, 1
	s_cmp_lt_u32 s3, 0x100000
	s_cbranch_scc1 .Lsb_loop2
.Lsb_done2:
	s_waitcnt vmcnt(0)
.LBB0_338:
	s_or_b64 exec, exec, s[8:9]
	s_waitcnt lgkmcnt(0)
	s_barrier

.Lsb_loop3:
	global_load_dword v3, v5, s[12:13] sc1
	s_waitcnt vmcnt(0)
	v_cmp_ge_u32_e32 vcc, v3, v4
	s_cbranch_vccnz .Lsb_done3
	s_sleep 1
	s_add_i32 s3, s3, 1
	s_cmp_lt_u32 s3, 0x100000
	s_cbranch_scc1 .Lsb_loop3
.Lsb_done3:
	s_waitcnt vmcnt(0)
.LBB0_405:
	s_or_b64 exec, exec, s[8:9]
	s_waitcnt lgkmcnt(0)
	s_barrier

.LBB0_430:
	s_or_b64 exec, exec, s[14:15]
	buffer_inv sc1
	v_cvt_f32_u32_e32 v4, v2
	s_waitcnt vmcnt(1)
	v_readfirstlane_b32 s3, v3
	v_sub_u32_e32 v3, 0, v2
	v_rcp_iflag_f32_e32 v4, v4
	v_add_u32_e32 v5, s3, v1
	v_mul_f32_e32 v4, 0x4f7ffffe, v4
	v_cvt_u32_f32_e32 v4, v4
	v_mul_lo_u32 v1, v3, v4
	v_mul_hi_u32 v1, v4, v1
	v_add_u32_e32 v1, v4, v1
	v_mul_hi_u32 v1, v5, v1
	v_mul_lo_u32 v3, v1, v2
	v_sub_u32_e32 v3, v5, v3
	v_add_u32_e32 v4, 1, v1
	v_cmp_ge_u32_e32 vcc, v3, v2
	s_nop 1
	v_cndmask_b32_e32 v1, v1, v4, vcc
	v_sub_u32_e32 v4, v3, v2
	v_cndmask_b32_e32 v3, v3, v4, vcc
	v_add_u32_e32 v4, 1, v1
	v_cmp_ge_u32_e32 vcc, v3, v2
	v_add_u32_e32 v3, 1, v5
	s_nop 0
	v_cndmask_b32_e32 v1, v1, v4, vcc
	v_mul_lo_u32 v4, v2, v1
	v_add_u32_e32 v2, v4, v2
	v_cmp_ne_u32_e32 vcc, v3, v2
	s_waitcnt lgkmcnt(0)
	v_mul_lo_u32 v4, v1, v0
	v_add_u32_e32 v4, v4, v0
	v_mov_b32_e32 v5, 0x2480
	s_cbranch_vccnz .Lsb_poll4
	buffer_wbl2 sc1
	s_waitcnt vmcnt(0)
	s_add_u32 s16, s4, 0x62480
	s_addc_u32 s17, s5, 0
	v_mov_b32_e32 v6, 0
	v_mov_b32_e32 v7, 1
	global_atomic_add v6, v7, s[16:17]
	global_atomic_add v6, v7, s[16:17] offset:256
	global_atomic_add v6, v7, s[16:17] offset:512
	global_atomic_add v6, v7, s[16:17] offset:768
	global_atomic_add v6, v7, s[16:17] offset:1024
	global_atomic_add v6, v7, s[16:17] offset:1280
	global_atomic_add v6, v7, s[16:17] offset:1536
	global_atomic_add v6, v7, s[16:17] offset:1792
	global_atomic_add v6, v7, s[16:17] offset:2048
	global_atomic_add v6, v7, s[16:17] offset:2304
	global_atomic_add v6, v7, s[16:17] offset:2560
	global_atomic_add v6, v7, s[16:17] offset:2816
	global_atomic_add v6, v7, s[16:17] offset:3072
	global_atomic_add v6, v7, s[16:17] offset:3328
	global_atomic_add v6, v7, s[16:17] offset:3584
	global_atomic_add v6, v7, s[16:17] offset:3840

.Lsb_loop4:
	global_load_dword v3, v5, s[10:11] sc1
	s_waitcnt vmcnt(0)
	v_cmp_ge_u32_e32 vcc, v3, v4
	s_cbranch_vccnz .Lsb_done4
	s_sleep 1
	s_add_i32 s3, s3, 1
	s_cmp_lt_u32 s3, 0x100000
	s_cbranch_scc1 .Lsb_loop4
.Lsb_done4:
	s_waitcnt vmcnt(0)
.LBB0_464:
	s_or_b64 exec, exec, s[8:9]
	s_waitcnt lgkmcnt(0)
	s_barrier
